# out-proj first K-iteration peeled too (SrcC=0, no zeroing v_movs)
# speedup vs baseline: 1.0261x; 1.0007x over previous
; #define PG8_STAGE(bufoff, gbase, voff) do { _Pragma("unroll") for (int _i = 0; _i < 2; ++_i) \
;         __builtin_amdgcn_global_load_lds((const unsigned*)((const char*)(gbase) + (voff)[_i]), (LAS unsigned*)(lds + (bufoff) + ldsw + _i * 8192), 16, 0, 0); } while (0)
; #define PG8_LDA(dst, b, h) do { _Pragma("unroll") for (int m = 0; m < 4; ++m) _Pragma("unroll") for (int k = 0; k < 2; ++k) dst[m][k] = *(const LAS bf16x8*)(lds + PG8_SA(b, h) + aoff + m * 2048 + k * 1024); } while (0)
; #define PG8_LDB(dst, b, h) do { _Pragma("unroll") for (int n = 0; n < 2; ++n) _Pragma("unroll") for (int k = 0; k < 2; ++k) dst[n][k] = *(const LAS bf16x8*)(lds + PG8_SB(b, h) + boff + n * 2048 + k * 1024); } while (0)
; #define PG8_MMA(ai, bj, At, Bt) do { __builtin_amdgcn_s_setprio(1); _Pragma("unroll") for (int m = 0; m < 4; ++m) _Pragma("unroll") for (int n = 0; n < 2; ++n) _Pragma("unroll") for (int k = 0; k < 2; ++k) \
;         acc[ai][bj][m][n] = __builtin_amdgcn_mfma_f32_16x16x32_bf16(Bt[n][k], At[m][k], acc[ai][bj][m][n], 0, 0, 0); __builtin_amdgcn_s_setprio(0); } while (0)
; #define PG8_WAIT_V(n) asm volatile("s_waitcnt vmcnt(" #n ")" ::: "memory")
; #define PG8_WAIT_L(n) asm volatile("s_waitcnt lgkmcnt(" #n ")" ::: "memory")
; #define PG8_BAR __builtin_amdgcn_s_barrier()
; #define PG8_SCHED __builtin_amdgcn_sched_barrier(0)
; template <class Prog>
; __device__ __forceinline__ void gemm_phase(LAS unsigned char* lds, const int K, const Prog& S) {
;     ...
;     f32x4 acc[2][2][4][2];
; #pragma unroll
;     for (int a = 0; a < 2; ++a)
; #pragma unroll
;         for (int b = 0; b < 2; ++b)
; #pragma unroll
;             for (int m = 0; m < 4; ++m)
; #pragma unroll
;                 for (int n = 0; n < 2; ++n) acc[a][b][m][n] = (f32x4){0.f, 0.f, 0.f, 0.f};
;     ...
;             PG8_LDB(B0, 0, 0); PG8_SCHED; PG8_LDA(At, 0, 0); PG8_STAGE(PG8_SA(1, 1), a1 + hstep, voffA);
;             PG8_WAIT_L(8); PG8_BAR; PG8_WAIT_L(0); PG8_MMA(0, 0, At, B0); PG8_BAR; PG8_SCHED;
;             PG8_LDB(B1, 0, 1); PG8_STAGE(PG8_SB(0, 0), b2, voffB);
;             PG8_BAR; PG8_WAIT_L(0); PG8_MMA(0, 1, At, B1); PG8_BAR;
;             PG8_LDA(At, 0, 1); PG8_STAGE(PG8_SA(0, 0), a2, voffA);
;             PG8_BAR; PG8_WAIT_L(0); PG8_MMA(1, 0, At, B0); PG8_BAR; PG8_SCHED;
;             PG8_STAGE(PG8_SB(0, 1), b2 + hstep, voffB);
;             PG8_WAIT_V(6); PG8_BAR; PG8_MMA(1, 1, At, B1); PG8_BAR;
.LBB0_570:
	s_add_u32 s46, s46, 0x80080
	s_addc_u32 s47, s47, 0
	s_add_u32 s41, s52, 0x100
	s_addc_u32 s43, s53, 0
	s_mov_b32 s54, -2
	s_waitcnt lgkmcnt(0)
	s_waitcnt vmcnt(16)
	v_add_u32_e32 v202, 0x10000, v215
	s_add_u32 s52, s46, 0xfff80080
	s_addc_u32 s53, s47, -1
	s_cmp_eq_u32 s54, 28
	s_cselect_b32 s93, s7, s53
	s_cselect_b32 s92, s6, s52
	s_cselect_b32 s53, s45, s43
	s_cselect_b32 s52, s44, s41
	s_add_u32 vcc_lo, s46, 0xfff80000
	s_addc_u32 vcc_hi, s47, -1
	ds_read_b128 v[128:131], v202
	ds_read_b128 v[132:135], v202 offset:1024
	ds_read_b128 v[136:139], v202 offset:2048
	ds_read_b128 v[140:143], v202 offset:3072
	s_add_i32 m0, s75, 0x8000
	ds_read_b128 v[176:179], v202 offset:16384
	ds_read_b128 v[180:183], v202 offset:17408
	ds_read_b128 v[184:187], v202 offset:18432
	ds_read_b128 v[198:201], v202 offset:19456
	global_load_lds_dwordx4 v190, vcc
	s_add_i32 m0, s75, 0xa000
	ds_read_b128 v[144:147], v217
	ds_read_b128 v[148:151], v217 offset:1024
	ds_read_b128 v[152:155], v217 offset:2048
	ds_read_b128 v[156:159], v217 offset:3072
	global_load_lds_dwordx4 v196, vcc
	s_add_i32 m0, s75, 0xc000
	ds_read_b128 v[160:163], v217 offset:4096
	ds_read_b128 v[164:167], v217 offset:5120
	ds_read_b128 v[168:171], v217 offset:6144
	ds_read_b128 v[172:175], v217 offset:7168
	global_load_lds_dwordx4 v190, s[46:47]
	s_add_i32 m0, s75, 0xe000
	s_nop 0
	global_load_lds_dwordx4 v196, s[46:47]
	s_waitcnt lgkmcnt(0)
	s_barrier
	v_mfma_f32_16x16x32_bf16 v[124:127], v[128:131], v[144:147], 0
	v_mfma_f32_16x16x32_bf16 v[120:123], v[136:139], v[144:147], 0
	v_mfma_f32_16x16x32_bf16 v[108:111], v[128:131], v[152:155], 0
	v_mfma_f32_16x16x32_bf16 v[104:107], v[136:139], v[152:155], 0
	v_mfma_f32_16x16x32_bf16 v[92:95], v[128:131], v[160:163], 0
	v_mfma_f32_16x16x32_bf16 v[88:91], v[136:139], v[160:163], 0
	v_mfma_f32_16x16x32_bf16 v[76:79], v[128:131], v[168:171], 0
	v_mfma_f32_16x16x32_bf16 v[72:75], v[136:139], v[168:171], 0
	v_mfma_f32_16x16x32_bf16 v[124:127], v[132:135], v[148:151], v[124:127]
	v_mfma_f32_16x16x32_bf16 v[120:123], v[140:143], v[148:151], v[120:123]
	v_mfma_f32_16x16x32_bf16 v[108:111], v[132:135], v[156:159], v[108:111]
	v_mfma_f32_16x16x32_bf16 v[104:107], v[140:143], v[156:159], v[104:107]
	v_mfma_f32_16x16x32_bf16 v[92:95], v[132:135], v[164:167], v[92:95]
	v_mfma_f32_16x16x32_bf16 v[88:91], v[140:143], v[164:167], v[88:91]
	v_mfma_f32_16x16x32_bf16 v[76:79], v[132:135], v[172:175], v[76:79]
	v_mfma_f32_16x16x32_bf16 v[72:75], v[140:143], v[172:175], v[72:75]
	v_mfma_f32_16x16x32_bf16 v[116:119], v[176:179], v[144:147], 0
	v_mfma_f32_16x16x32_bf16 v[112:115], v[184:187], v[144:147], 0
	v_mfma_f32_16x16x32_bf16 v[100:103], v[176:179], v[152:155], 0
	v_mfma_f32_16x16x32_bf16 v[96:99], v[184:187], v[152:155], 0
	v_mfma_f32_16x16x32_bf16 v[84:87], v[176:179], v[160:163], 0
	v_mfma_f32_16x16x32_bf16 v[80:83], v[184:187], v[160:163], 0
	v_mfma_f32_16x16x32_bf16 v[68:71], v[176:179], v[168:171], 0
	v_mfma_f32_16x16x32_bf16 v[64:67], v[184:187], v[168:171], 0
	v_mfma_f32_16x16x32_bf16 v[116:119], v[180:183], v[148:151], v[116:119]
	v_mfma_f32_16x16x32_bf16 v[112:115], v[198:201], v[148:151], v[112:115]
	v_mfma_f32_16x16x32_bf16 v[100:103], v[180:183], v[156:159], v[100:103]
	v_mfma_f32_16x16x32_bf16 v[96:99], v[198:201], v[156:159], v[96:99]
	v_mfma_f32_16x16x32_bf16 v[84:87], v[180:183], v[164:167], v[84:87]
	v_mfma_f32_16x16x32_bf16 v[80:83], v[198:201], v[164:167], v[80:83]
	v_mfma_f32_16x16x32_bf16 v[68:71], v[180:183], v[172:175], v[68:71]
	v_mfma_f32_16x16x32_bf16 v[64:67], v[198:201], v[172:175], v[64:67]
	s_barrier
	ds_read_b128 v[144:147], v217 offset:16384
	ds_read_b128 v[148:151], v217 offset:17408
	ds_read_b128 v[152:155], v217 offset:18432
	ds_read_b128 v[156:159], v217 offset:19456
	s_add_i32 m0, s75, 0x10000
	ds_read_b128 v[160:163], v217 offset:20480
	ds_read_b128 v[164:167], v217 offset:21504
	ds_read_b128 v[168:171], v217 offset:22528
	ds_read_b128 v[172:175], v217 offset:23552
	global_load_lds_dwordx4 v192, s[52:53]
	s_add_i32 m0, s75, 0x12000
	s_nop 0
	global_load_lds_dwordx4 v188, s[52:53]
	s_add_u32 vcc_lo, s52, 0x80000
	s_addc_u32 vcc_hi, s53, 0
	s_add_i32 m0, s75, 0x14000
	s_nop 0
	global_load_lds_dwordx4 v192, vcc
	s_add_i32 m0, s75, 0x16000
	s_nop 0
	global_load_lds_dwordx4 v188, vcc
	s_waitcnt vmcnt(4)
	s_waitcnt lgkmcnt(0)
	s_barrier
	v_mfma_f32_16x16x32_bf16 v[60:63], v[128:131], v[144:147], 0
	v_mfma_f32_16x16x32_bf16 v[56:59], v[136:139], v[144:147], 0
	v_mfma_f32_16x16x32_bf16 v[44:47], v[128:131], v[152:155], 0
	v_mfma_f32_16x16x32_bf16 v[40:43], v[136:139], v[152:155], 0
	v_mfma_f32_16x16x32_bf16 v[28:31], v[128:131], v[160:163], 0
	v_mfma_f32_16x16x32_bf16 v[24:27], v[136:139], v[160:163], 0
	v_mfma_f32_16x16x32_bf16 v[12:15], v[128:131], v[168:171], 0
	v_mfma_f32_16x16x32_bf16 v[8:11], v[136:139], v[168:171], 0
	v_mfma_f32_16x16x32_bf16 v[60:63], v[132:135], v[148:151], v[60:63]
	v_mfma_f32_16x16x32_bf16 v[56:59], v[140:143], v[148:151], v[56:59]
	v_mfma_f32_16x16x32_bf16 v[44:47], v[132:135], v[156:159], v[44:47]
	v_mfma_f32_16x16x32_bf16 v[40:43], v[140:143], v[156:159], v[40:43]
	v_mfma_f32_16x16x32_bf16 v[28:31], v[132:135], v[164:167], v[28:31]
	v_mfma_f32_16x16x32_bf16 v[24:27], v[140:143], v[164:167], v[24:27]
	v_mfma_f32_16x16x32_bf16 v[12:15], v[132:135], v[172:175], v[12:15]
	v_mfma_f32_16x16x32_bf16 v[8:11], v[140:143], v[172:175], v[8:11]
	v_mfma_f32_16x16x32_bf16 v[52:55], v[176:179], v[144:147], 0
	v_mfma_f32_16x16x32_bf16 v[48:51], v[184:187], v[144:147], 0
	v_mfma_f32_16x16x32_bf16 v[36:39], v[176:179], v[152:155], 0
	v_mfma_f32_16x16x32_bf16 v[32:35], v[184:187], v[152:155], 0
	v_mfma_f32_16x16x32_bf16 v[20:23], v[176:179], v[160:163], 0
	v_mfma_f32_16x16x32_bf16 v[16:19], v[184:187], v[160:163], 0
	v_mfma_f32_16x16x32_bf16 v[4:7], v[176:179], v[168:171], 0
	v_mfma_f32_16x16x32_bf16 v[0:3], v[184:187], v[168:171], 0
	v_mfma_f32_16x16x32_bf16 v[52:55], v[180:183], v[148:151], v[52:55]
	v_mfma_f32_16x16x32_bf16 v[48:51], v[198:201], v[148:151], v[48:51]
	v_mfma_f32_16x16x32_bf16 v[36:39], v[180:183], v[156:159], v[36:39]
	v_mfma_f32_16x16x32_bf16 v[32:35], v[198:201], v[156:159], v[32:35]
	v_mfma_f32_16x16x32_bf16 v[20:23], v[180:183], v[164:167], v[20:23]
	v_mfma_f32_16x16x32_bf16 v[16:19], v[198:201], v[164:167], v[16:19]
	v_mfma_f32_16x16x32_bf16 v[4:7], v[180:183], v[172:175], v[4:7]
	v_mfma_f32_16x16x32_bf16 v[0:3], v[198:201], v[172:175], v[0:3]
	s_barrier
; #define PG8_STAGE(bufoff, gbase, voff) do { _Pragma("unroll") for (int _i = 0; _i < 2; ++_i) \
;         __builtin_amdgcn_global_load_lds((const unsigned*)((const char*)(gbase) + (voff)[_i]), (LAS unsigned*)(lds + (bufoff) + ldsw + _i * 8192), 16, 0, 0); } while (0)
; #define PG8_LDA(dst, b, h) do { _Pragma("unroll") for (int m = 0; m < 4; ++m) _Pragma("unroll") for (int k = 0; k < 2; ++k) dst[m][k] = *(const LAS bf16x8*)(lds + PG8_SA(b, h) + aoff + m * 2048 + k * 1024); } while (0)
; #define PG8_LDB(dst, b, h) do { _Pragma("unroll") for (int n = 0; n < 2; ++n) _Pragma("unroll") for (int k = 0; k < 2; ++k) dst[n][k] = *(const LAS bf16x8*)(lds + PG8_SB(b, h) + boff + n * 2048 + k * 1024); } while (0)
; #define PG8_MMA(ai, bj, At, Bt) do { __builtin_amdgcn_s_setprio(1); _Pragma("unroll") for (int m = 0; m < 4; ++m) _Pragma("unroll") for (int n = 0; n < 2; ++n) _Pragma("unroll") for (int k = 0; k < 2; ++k) \
;         acc[ai][bj][m][n] = __builtin_amdgcn_mfma_f32_16x16x32_bf16(Bt[n][k], At[m][k], acc[ai][bj][m][n], 0, 0, 0); __builtin_amdgcn_s_setprio(0); } while (0)
; #define PG8_WAIT_V(n) asm volatile("s_waitcnt vmcnt(" #n ")" ::: "memory")
; #define PG8_WAIT_L(n) asm volatile("s_waitcnt lgkmcnt(" #n ")" ::: "memory")
; #define PG8_BAR __builtin_amdgcn_s_barrier()
; #define PG8_SCHED __builtin_amdgcn_sched_barrier(0)
; template <class Prog>
; __device__ __forceinline__ void gemm_phase(LAS unsigned char* lds, const int K, const Prog& S) {
;     ...
;             PG8_LDB(B0, 1, 0); PG8_SCHED; PG8_LDA(At, 1, 0); PG8_STAGE(PG8_SA(0, 1), a2 + hstep, voffA);
;             PG8_WAIT_L(8); PG8_BAR; PG8_WAIT_L(0); PG8_MMA(0, 0, At, B0); PG8_BAR; PG8_SCHED;
;             PG8_LDB(B1, 1, 1); PG8_STAGE(PG8_SB(1, 0), b3, voffB);
;             PG8_BAR; PG8_WAIT_L(0); PG8_MMA(0, 1, At, B1); PG8_BAR;
;             PG8_LDA(At, 1, 1); PG8_STAGE(PG8_SA(1, 0), a3, voffA);
;             PG8_BAR; PG8_WAIT_L(0); PG8_MMA(1, 0, At, B0); PG8_BAR; PG8_SCHED;
;             PG8_STAGE(PG8_SB(1, 1), b3 + hstep, voffB);
;             PG8_WAIT_V(6); PG8_BAR; PG8_MMA(1, 1, At, B1); PG8_BAR;
	s_add_u32 vcc_lo, s92, 0x80000
	s_addc_u32 vcc_hi, s93, 0
	ds_read_b128 v[128:131], v202 offset:32768
	ds_read_b128 v[132:135], v202 offset:33792
	ds_read_b128 v[136:139], v202 offset:34816
	ds_read_b128 v[140:143], v202 offset:35840
	s_mov_b32 m0, s75
	ds_read_b128 v[176:179], v202 offset:49152
	ds_read_b128 v[180:183], v202 offset:50176
	ds_read_b128 v[184:187], v202 offset:51200
	ds_read_b128 v[198:201], v202 offset:52224
	global_load_lds_dwordx4 v192, s[92:93]
	s_add_i32 m0, s75, 0x2000
	ds_read_b128 v[144:147], v217 offset:32768
	ds_read_b128 v[148:151], v217 offset:33792
	ds_read_b128 v[152:155], v217 offset:34816
	ds_read_b128 v[156:159], v217 offset:35840
	global_load_lds_dwordx4 v188, s[92:93]
	s_add_i32 m0, s75, 0x4000
	ds_read_b128 v[160:163], v217 offset:36864
	ds_read_b128 v[164:167], v217 offset:37888
	ds_read_b128 v[168:171], v217 offset:38912
	ds_read_b128 v[172:175], v217 offset:39936
	global_load_lds_dwordx4 v192, vcc
	s_add_i32 m0, s75, 0x6000
	s_nop 0
	global_load_lds_dwordx4 v188, vcc
	s_waitcnt lgkmcnt(0)
	s_barrier
	v_mfma_f32_16x16x32_bf16 v[124:127], v[128:131], v[144:147], v[124:127]
	v_mfma_f32_16x16x32_bf16 v[120:123], v[136:139], v[144:147], v[120:123]
	v_mfma_f32_16x16x32_bf16 v[108:111], v[128:131], v[152:155], v[108:111]
	v_mfma_f32_16x16x32_bf16 v[104:107], v[136:139], v[152:155], v[104:107]
	v_mfma_f32_16x16x32_bf16 v[92:95], v[128:131], v[160:163], v[92:95]
	v_mfma_f32_16x16x32_bf16 v[88:91], v[136:139], v[160:163], v[88:91]
	v_mfma_f32_16x16x32_bf16 v[76:79], v[128:131], v[168:171], v[76:79]
	v_mfma_f32_16x16x32_bf16 v[72:75], v[136:139], v[168:171], v[72:75]
	v_mfma_f32_16x16x32_bf16 v[124:127], v[132:135], v[148:151], v[124:127]
	v_mfma_f32_16x16x32_bf16 v[120:123], v[140:143], v[148:151], v[120:123]
	v_mfma_f32_16x16x32_bf16 v[108:111], v[132:135], v[156:159], v[108:111]
	v_mfma_f32_16x16x32_bf16 v[104:107], v[140:143], v[156:159], v[104:107]
	v_mfma_f32_16x16x32_bf16 v[92:95], v[132:135], v[164:167], v[92:95]
	v_mfma_f32_16x16x32_bf16 v[88:91], v[140:143], v[164:167], v[88:91]
	v_mfma_f32_16x16x32_bf16 v[76:79], v[132:135], v[172:175], v[76:79]
	v_mfma_f32_16x16x32_bf16 v[72:75], v[140:143], v[172:175], v[72:75]
	v_mfma_f32_16x16x32_bf16 v[116:119], v[176:179], v[144:147], v[116:119]
	v_mfma_f32_16x16x32_bf16 v[112:115], v[184:187], v[144:147], v[112:115]
	v_mfma_f32_16x16x32_bf16 v[100:103], v[176:179], v[152:155], v[100:103]
	v_mfma_f32_16x16x32_bf16 v[96:99], v[184:187], v[152:155], v[96:99]
	v_mfma_f32_16x16x32_bf16 v[84:87], v[176:179], v[160:163], v[84:87]
	v_mfma_f32_16x16x32_bf16 v[80:83], v[184:187], v[160:163], v[80:83]
	v_mfma_f32_16x16x32_bf16 v[68:71], v[176:179], v[168:171], v[68:71]
	v_mfma_f32_16x16x32_bf16 v[64:67], v[184:187], v[168:171], v[64:67]
	v_mfma_f32_16x16x32_bf16 v[116:119], v[180:183], v[148:151], v[116:119]
	v_mfma_f32_16x16x32_bf16 v[112:115], v[198:201], v[148:151], v[112:115]
	v_mfma_f32_16x16x32_bf16 v[100:103], v[180:183], v[156:159], v[100:103]
	v_mfma_f32_16x16x32_bf16 v[96:99], v[198:201], v[156:159], v[96:99]
	v_mfma_f32_16x16x32_bf16 v[84:87], v[180:183], v[164:167], v[84:87]
	v_mfma_f32_16x16x32_bf16 v[80:83], v[198:201], v[164:167], v[80:83]
	v_mfma_f32_16x16x32_bf16 v[68:71], v[180:183], v[172:175], v[68:71]
	v_mfma_f32_16x16x32_bf16 v[64:67], v[198:201], v[172:175], v[64:67]
	s_barrier
	s_add_u32 vcc_lo, s52, 0x80
	s_addc_u32 vcc_hi, s53, 0
	ds_read_b128 v[144:147], v217 offset:49152
	ds_read_b128 v[148:151], v217 offset:50176
	ds_read_b128 v[152:155], v217 offset:51200
	ds_read_b128 v[156:159], v217 offset:52224
	s_add_i32 m0, s75, 0x18000
	ds_read_b128 v[160:163], v217 offset:53248
	ds_read_b128 v[164:167], v217 offset:54272
	ds_read_b128 v[168:171], v217 offset:55296
	ds_read_b128 v[172:175], v217 offset:56320
	global_load_lds_dwordx4 v192, vcc
	s_add_i32 m0, s75, 0x1a000
	s_nop 0
	global_load_lds_dwordx4 v188, vcc
	s_add_u32 vcc_lo, s52, 0x80080
	s_addc_u32 vcc_hi, s53, 0
	s_add_i32 m0, s75, 0x1c000
	s_nop 0
	global_load_lds_dwordx4 v192, vcc
	s_add_i32 m0, s75, 0x1e000
	s_nop 0
	global_load_lds_dwordx4 v188, vcc
	s_waitcnt vmcnt(4)
	s_waitcnt lgkmcnt(0)
	s_barrier
	v_mfma_f32_16x16x32_bf16 v[60:63], v[128:131], v[144:147], v[60:63]
	v_mfma_f32_16x16x32_bf16 v[56:59], v[136:139], v[144:147], v[56:59]
	v_mfma_f32_16x16x32_bf16 v[44:47], v[128:131], v[152:155], v[44:47]
	v_mfma_f32_16x16x32_bf16 v[40:43], v[136:139], v[152:155], v[40:43]
	v_mfma_f32_16x16x32_bf16 v[28:31], v[128:131], v[160:163], v[28:31]
	v_mfma_f32_16x16x32_bf16 v[24:27], v[136:139], v[160:163], v[24:27]
	v_mfma_f32_16x16x32_bf16 v[12:15], v[128:131], v[168:171], v[12:15]
	v_mfma_f32_16x16x32_bf16 v[8:11], v[136:139], v[168:171], v[8:11]
	v_mfma_f32_16x16x32_bf16 v[60:63], v[132:135], v[148:151], v[60:63]
	v_mfma_f32_16x16x32_bf16 v[56:59], v[140:143], v[148:151], v[56:59]
	v_mfma_f32_16x16x32_bf16 v[44:47], v[132:135], v[156:159], v[44:47]
	v_mfma_f32_16x16x32_bf16 v[40:43], v[140:143], v[156:159], v[40:43]
	v_mfma_f32_16x16x32_bf16 v[28:31], v[132:135], v[164:167], v[28:31]
	v_mfma_f32_16x16x32_bf16 v[24:27], v[140:143], v[164:167], v[24:27]
	v_mfma_f32_16x16x32_bf16 v[12:15], v[132:135], v[172:175], v[12:15]
	v_mfma_f32_16x16x32_bf16 v[8:11], v[140:143], v[172:175], v[8:11]
	v_mfma_f32_16x16x32_bf16 v[52:55], v[176:179], v[144:147], v[52:55]
	v_mfma_f32_16x16x32_bf16 v[48:51], v[184:187], v[144:147], v[48:51]
	v_mfma_f32_16x16x32_bf16 v[36:39], v[176:179], v[152:155], v[36:39]
	v_mfma_f32_16x16x32_bf16 v[32:35], v[184:187], v[152:155], v[32:35]
	v_mfma_f32_16x16x32_bf16 v[20:23], v[176:179], v[160:163], v[20:23]
	v_mfma_f32_16x16x32_bf16 v[16:19], v[184:187], v[160:163], v[16:19]
	v_mfma_f32_16x16x32_bf16 v[4:7], v[176:179], v[168:171], v[4:7]
	v_mfma_f32_16x16x32_bf16 v[0:3], v[184:187], v[168:171], v[0:3]
	v_mfma_f32_16x16x32_bf16 v[52:55], v[180:183], v[148:151], v[52:55]
	v_mfma_f32_16x16x32_bf16 v[48:51], v[198:201], v[148:151], v[48:51]
	v_mfma_f32_16x16x32_bf16 v[36:39], v[180:183], v[156:159], v[36:39]
	v_mfma_f32_16x16x32_bf16 v[32:35], v[198:201], v[156:159], v[32:35]
	v_mfma_f32_16x16x32_bf16 v[20:23], v[180:183], v[164:167], v[20:23]
	v_mfma_f32_16x16x32_bf16 v[16:19], v[198:201], v[164:167], v[16:19]
	v_mfma_f32_16x16x32_bf16 v[4:7], v[180:183], v[172:175], v[4:7]
	v_mfma_f32_16x16x32_bf16 v[0:3], v[198:201], v[172:175], v[0:3]
	s_add_i32 s54, s54, 2
	s_add_u32 s46, s46, 0x100
	s_addc_u32 s47, s47, 0
	s_add_u32 s41, s41, 0x100
	s_addc_u32 s43, s43, 0
	s_cmp_gt_u32 s54, 29
	s_barrier
	.p2align 6
